# tile start: first MFMA section's 16 LDS fragment reads issued at the top of the tile header
# baseline (speedup 1.0000x reference)
.LBB0_285:
	v_add_u32_e32 v166, 0x10000, v147
	v_add_u32_e32 v182, 0x14000, v147
	ds_read_b128 v[142:145], v166
	ds_read_b128 v[158:161], v166 offset:1024
	ds_read_b128 v[162:165], v166 offset:2048
	ds_read_b128 v[166:169], v166 offset:3072
	ds_read_b128 v[170:173], v182
	ds_read_b128 v[174:177], v182 offset:1024
	ds_read_b128 v[178:181], v182 offset:2048
	ds_read_b128 v[182:185], v182 offset:3072
	ds_read_b128 v[186:189], v157
	ds_read_b128 v[190:193], v157 offset:1024
	ds_read_b128 v[194:197], v157 offset:2048
	ds_read_b128 v[198:201], v157 offset:3072
	ds_read_b128 v[202:205], v157 offset:4096
	ds_read_b128 v[206:209], v157 offset:5120
	ds_read_b128 v[220:223], v157 offset:6144
	ds_read_b128 v[236:239], v157 offset:7168
	s_add_i32 s54, s9, 1
	s_mul_i32 s6, s54, s52
	s_mul_hi_u32 s7, s54, s98
	s_add_i32 s7, s7, s6
	s_mul_i32 s6, s54, s98
	v_readlane_b32 s22, v254, 47
	v_readlane_b32 s23, v254, 48
	s_add_u32 s22, s6, s22
	s_addc_u32 s23, s7, s53
	v_cmp_gt_i64_e32 vcc, s[22:23], v[212:213]
	v_cmp_lt_i64_e64 s[6:7], s[22:23], v[210:211]
	s_cbranch_vccnz .LBB0_287
	s_cmpk_lg_i32 s98, 0x100
	s_cbranch_scc1 .Lkq_dec_gen
	s_add_i32 s18, s26, 4
	s_mov_b32 s20, s8
	s_branch .LBB0_287

.LBB0_287:
	s_ashr_i32 s21, s20, 31
	s_lshl_b64 s[22:23], s[20:21], 19
	s_add_u32 s22, s80, s22
	s_addc_u32 s23, s81, s23
	s_and_b64 s[24:25], s[6:7], exec
	s_cselect_b32 s21, s23, s29
	s_cselect_b32 s36, s22, s28
	s_ashr_i32 s19, s18, 31
	s_lshl_b64 s[24:25], s[18:19], 19
	s_add_u32 s24, s40, s24
	s_addc_u32 s25, s41, s25
	s_and_b64 s[34:35], s[6:7], exec
	s_cselect_b32 s19, s25, s31
	s_cselect_b32 s37, s24, s30
	s_add_u32 s38, s30, 0x100
	s_addc_u32 s39, s31, 0
	s_add_u32 s28, s28, 0x40080
	s_addc_u32 s29, s29, 0
	s_mov_b32 s55, -2
	s_add_u32 s30, s28, 0xfffc0080
	s_addc_u32 s31, s29, -1
	s_add_i32 s56, 0, 0x10000
	s_cmp_eq_u32 s55, 12
	s_cselect_b32 s35, s21, s31
	s_cselect_b32 s34, s36, s30
	s_cselect_b32 s31, s19, s39
	s_cselect_b32 s30, s37, s38
	s_add_i32 s58, 0, 0x14000
	v_lshl_add_u64 v[224:225], s[28:29], 0, v[140:141]
	s_add_i32 m0, s44, 0xc000
	global_load_lds_dwordx4 v[224:225], off
	v_lshl_add_u64 v[224:225], s[28:29], 0, v[138:139]
	s_add_i32 m0, s44, 0xe000
	s_nop 0
	global_load_lds_dwordx4 v[224:225], off
	s_nop 0
	s_nop 0
	s_nop 0
	s_nop 0
	s_nop 0
	s_nop 0
	s_nop 0
	s_nop 0
	s_nop 0
	s_nop 0
	s_nop 0
	s_nop 0
	s_nop 0
	s_nop 0
	s_nop 0
	s_nop 0
	s_nop 0
	s_waitcnt vmcnt(8)
	s_waitcnt lgkmcnt(0)
	s_barrier
	s_waitcnt lgkmcnt(0)
	v_mfma_f32_16x16x32_bf16 v[126:129], v[142:145], v[186:189], 0
	v_mfma_f32_16x16x32_bf16 v[122:125], v[162:165], v[186:189], 0
	v_mfma_f32_16x16x32_bf16 v[110:113], v[142:145], v[194:197], 0
	v_mfma_f32_16x16x32_bf16 v[106:109], v[162:165], v[194:197], 0
	v_mfma_f32_16x16x32_bf16 v[94:97], v[142:145], v[202:205], 0
	v_mfma_f32_16x16x32_bf16 v[90:93], v[162:165], v[202:205], 0
	v_mfma_f32_16x16x32_bf16 v[78:81], v[142:145], v[220:223], 0
	v_mfma_f32_16x16x32_bf16 v[74:77], v[162:165], v[220:223], 0
	v_mfma_f32_16x16x32_bf16 v[126:129], v[158:161], v[190:193], v[126:129]
	v_mfma_f32_16x16x32_bf16 v[122:125], v[166:169], v[190:193], v[122:125]
	v_mfma_f32_16x16x32_bf16 v[110:113], v[158:161], v[198:201], v[110:113]
	v_mfma_f32_16x16x32_bf16 v[106:109], v[166:169], v[198:201], v[106:109]
	v_mfma_f32_16x16x32_bf16 v[94:97], v[158:161], v[206:209], v[94:97]
	v_mfma_f32_16x16x32_bf16 v[90:93], v[166:169], v[206:209], v[90:93]
	v_mfma_f32_16x16x32_bf16 v[78:81], v[158:161], v[236:239], v[78:81]
	v_mfma_f32_16x16x32_bf16 v[74:77], v[166:169], v[236:239], v[74:77]
	v_mfma_f32_16x16x32_bf16 v[118:121], v[170:173], v[186:189], 0
	v_mfma_f32_16x16x32_bf16 v[114:117], v[178:181], v[186:189], 0
	v_mfma_f32_16x16x32_bf16 v[102:105], v[170:173], v[194:197], 0
	v_mfma_f32_16x16x32_bf16 v[98:101], v[178:181], v[194:197], 0
	v_mfma_f32_16x16x32_bf16 v[86:89], v[170:173], v[202:205], 0
	v_mfma_f32_16x16x32_bf16 v[82:85], v[178:181], v[202:205], 0
	v_mfma_f32_16x16x32_bf16 v[70:73], v[170:173], v[220:223], 0
	v_mfma_f32_16x16x32_bf16 v[66:69], v[178:181], v[220:223], 0
	v_mfma_f32_16x16x32_bf16 v[118:121], v[174:177], v[190:193], v[118:121]
	v_mfma_f32_16x16x32_bf16 v[114:117], v[182:185], v[190:193], v[114:117]
	v_mfma_f32_16x16x32_bf16 v[102:105], v[174:177], v[198:201], v[102:105]
	v_mfma_f32_16x16x32_bf16 v[98:101], v[182:185], v[198:201], v[98:101]
	v_mfma_f32_16x16x32_bf16 v[86:89], v[174:177], v[206:209], v[86:89]
	v_mfma_f32_16x16x32_bf16 v[82:85], v[182:185], v[206:209], v[82:85]
	v_mfma_f32_16x16x32_bf16 v[70:73], v[174:177], v[236:239], v[70:73]
	v_mfma_f32_16x16x32_bf16 v[66:69], v[182:185], v[236:239], v[66:69]
	s_barrier
	s_add_i32 s56, s56, s27
	v_lshl_add_u64 v[224:225], s[30:31], 0, v[132:133]
	s_mov_b32 m0, s56
	ds_read_b128 v[186:189], v157 offset:16384
	ds_read_b128 v[190:193], v157 offset:17408
	ds_read_b128 v[194:197], v157 offset:18432
	ds_read_b128 v[198:201], v157 offset:19456
	ds_read_b128 v[202:205], v157 offset:20480
	ds_read_b128 v[206:209], v157 offset:21504
	ds_read_b128 v[220:223], v157 offset:22528
	ds_read_b128 v[236:239], v157 offset:23552
	global_load_lds_dwordx4 v[224:225], off
	s_add_i32 m0, s56, 0x2000
	s_add_u32 s56, s30, 0x40000
	v_lshl_add_u64 v[230:231], s[30:31], 0, v[136:137]
	s_addc_u32 s57, s31, 0
	s_add_i32 s58, s58, s27
	global_load_lds_dwordx4 v[230:231], off
	v_lshl_add_u64 v[240:241], s[56:57], 0, v[132:133]
	s_mov_b32 m0, s58
	v_lshl_add_u64 v[242:243], s[34:35], 0, v[134:135]
	global_load_lds_dwordx4 v[240:241], off
	v_lshl_add_u64 v[240:241], s[56:57], 0, v[136:137]
	s_add_i32 m0, s58, 0x2000
	s_nop 0
	global_load_lds_dwordx4 v[240:241], off
	v_lshl_add_u64 v[240:241], s[34:35], 0, v[130:131]
	s_mov_b32 m0, s44
	s_nop 0
	global_load_lds_dwordx4 v[240:241], off
	s_mov_b32 m0, s45
	s_nop 0
	global_load_lds_dwordx4 v[242:243], off
	s_nop 0
	s_nop 0
	s_nop 0
	s_waitcnt vmcnt(8)
	s_waitcnt lgkmcnt(0)
	s_barrier
	s_waitcnt lgkmcnt(0)
	v_mfma_f32_16x16x32_bf16 v[62:65], v[142:145], v[186:189], 0
	v_mfma_f32_16x16x32_bf16 v[58:61], v[162:165], v[186:189], 0
	v_mfma_f32_16x16x32_bf16 v[46:49], v[142:145], v[194:197], 0
	v_mfma_f32_16x16x32_bf16 v[42:45], v[162:165], v[194:197], 0
	v_mfma_f32_16x16x32_bf16 v[30:33], v[142:145], v[202:205], 0
	v_mfma_f32_16x16x32_bf16 v[26:29], v[162:165], v[202:205], 0
	v_mfma_f32_16x16x32_bf16 v[14:17], v[142:145], v[220:223], 0
	v_mfma_f32_16x16x32_bf16 v[10:13], v[162:165], v[220:223], 0
	v_mfma_f32_16x16x32_bf16 v[62:65], v[158:161], v[190:193], v[62:65]
	v_mfma_f32_16x16x32_bf16 v[58:61], v[166:169], v[190:193], v[58:61]
	v_mfma_f32_16x16x32_bf16 v[46:49], v[158:161], v[198:201], v[46:49]
	v_mfma_f32_16x16x32_bf16 v[42:45], v[166:169], v[198:201], v[42:45]
	v_mfma_f32_16x16x32_bf16 v[30:33], v[158:161], v[206:209], v[30:33]
	v_mfma_f32_16x16x32_bf16 v[26:29], v[166:169], v[206:209], v[26:29]
	v_mfma_f32_16x16x32_bf16 v[14:17], v[158:161], v[236:239], v[14:17]
	v_mfma_f32_16x16x32_bf16 v[10:13], v[166:169], v[236:239], v[10:13]
	v_mfma_f32_16x16x32_bf16 v[54:57], v[170:173], v[186:189], 0
	v_mfma_f32_16x16x32_bf16 v[50:53], v[178:181], v[186:189], 0
	v_mfma_f32_16x16x32_bf16 v[38:41], v[170:173], v[194:197], 0
	v_mfma_f32_16x16x32_bf16 v[34:37], v[178:181], v[194:197], 0
	v_mfma_f32_16x16x32_bf16 v[22:25], v[170:173], v[202:205], 0
	v_mfma_f32_16x16x32_bf16 v[18:21], v[178:181], v[202:205], 0
	v_mfma_f32_16x16x32_bf16 v[6:9], v[170:173], v[220:223], 0
	v_mfma_f32_16x16x32_bf16 v[2:5], v[178:181], v[220:223], 0
	v_mfma_f32_16x16x32_bf16 v[54:57], v[174:177], v[190:193], v[54:57]
	v_mfma_f32_16x16x32_bf16 v[50:53], v[182:185], v[190:193], v[50:53]
	v_mfma_f32_16x16x32_bf16 v[38:41], v[174:177], v[198:201], v[38:41]
	v_mfma_f32_16x16x32_bf16 v[34:37], v[182:185], v[198:201], v[34:37]
	v_mfma_f32_16x16x32_bf16 v[22:25], v[174:177], v[206:209], v[22:25]
	v_mfma_f32_16x16x32_bf16 v[18:21], v[182:185], v[206:209], v[18:21]
	v_mfma_f32_16x16x32_bf16 v[6:9], v[174:177], v[236:239], v[6:9]
	v_mfma_f32_16x16x32_bf16 v[2:5], v[182:185], v[236:239], v[2:5]
	s_barrier
	s_add_i32 s56, 0, 0x18000
	s_add_i32 s57, 0, 0x1c000
	v_add_u32_e32 v166, s56, v147
	v_add_u32_e32 v182, s57, v147
	ds_read_b128 v[142:145], v166
	ds_read_b128 v[158:161], v166 offset:1024
	ds_read_b128 v[162:165], v166 offset:2048
	ds_read_b128 v[166:169], v166 offset:3072
	ds_read_b128 v[170:173], v182
	ds_read_b128 v[174:177], v182 offset:1024
	ds_read_b128 v[178:181], v182 offset:2048
	ds_read_b128 v[182:185], v182 offset:3072
	s_add_u32 s34, s34, 0x40000
	s_addc_u32 s35, s35, 0
	s_mov_b32 m0, s43
	v_lshl_add_u64 v[244:245], s[34:35], 0, v[130:131]
	ds_read_b128 v[186:189], v157 offset:32768
	ds_read_b128 v[190:193], v157 offset:33792
	ds_read_b128 v[194:197], v157 offset:34816
	ds_read_b128 v[198:201], v157 offset:35840
	ds_read_b128 v[202:205], v157 offset:36864
	ds_read_b128 v[206:209], v157 offset:37888
	ds_read_b128 v[220:223], v157 offset:38912
	ds_read_b128 v[236:239], v157 offset:39936
	global_load_lds_dwordx4 v[244:245], off
	v_lshl_add_u64 v[244:245], s[34:35], 0, v[134:135]
	s_mov_b32 m0, s46
	s_nop 0
	global_load_lds_dwordx4 v[244:245], off
	s_nop 0
	s_nop 0
	s_nop 0
	s_nop 0
	s_nop 0
	s_nop 0
	s_nop 0
	s_waitcnt vmcnt(8)
	s_waitcnt lgkmcnt(0)
	s_barrier
	s_waitcnt lgkmcnt(0)
	v_mfma_f32_16x16x32_bf16 v[126:129], v[142:145], v[186:189], v[126:129]
	v_mfma_f32_16x16x32_bf16 v[122:125], v[162:165], v[186:189], v[122:125]
	v_mfma_f32_16x16x32_bf16 v[110:113], v[142:145], v[194:197], v[110:113]
	v_mfma_f32_16x16x32_bf16 v[106:109], v[162:165], v[194:197], v[106:109]
	v_mfma_f32_16x16x32_bf16 v[94:97], v[142:145], v[202:205], v[94:97]
	v_mfma_f32_16x16x32_bf16 v[90:93], v[162:165], v[202:205], v[90:93]
	v_mfma_f32_16x16x32_bf16 v[78:81], v[142:145], v[220:223], v[78:81]
	v_mfma_f32_16x16x32_bf16 v[74:77], v[162:165], v[220:223], v[74:77]
	v_mfma_f32_16x16x32_bf16 v[126:129], v[158:161], v[190:193], v[126:129]
	v_mfma_f32_16x16x32_bf16 v[122:125], v[166:169], v[190:193], v[122:125]
	v_mfma_f32_16x16x32_bf16 v[110:113], v[158:161], v[198:201], v[110:113]
	v_mfma_f32_16x16x32_bf16 v[106:109], v[166:169], v[198:201], v[106:109]
	v_mfma_f32_16x16x32_bf16 v[94:97], v[158:161], v[206:209], v[94:97]
	v_mfma_f32_16x16x32_bf16 v[90:93], v[166:169], v[206:209], v[90:93]
	v_mfma_f32_16x16x32_bf16 v[78:81], v[158:161], v[236:239], v[78:81]
	v_mfma_f32_16x16x32_bf16 v[74:77], v[166:169], v[236:239], v[74:77]
	v_mfma_f32_16x16x32_bf16 v[118:121], v[170:173], v[186:189], v[118:121]
	v_mfma_f32_16x16x32_bf16 v[114:117], v[178:181], v[186:189], v[114:117]
	v_mfma_f32_16x16x32_bf16 v[102:105], v[170:173], v[194:197], v[102:105]
	v_mfma_f32_16x16x32_bf16 v[98:101], v[178:181], v[194:197], v[98:101]
	v_mfma_f32_16x16x32_bf16 v[86:89], v[170:173], v[202:205], v[86:89]
	v_mfma_f32_16x16x32_bf16 v[82:85], v[178:181], v[202:205], v[82:85]
	v_mfma_f32_16x16x32_bf16 v[70:73], v[170:173], v[220:223], v[70:73]
	v_mfma_f32_16x16x32_bf16 v[66:69], v[178:181], v[220:223], v[66:69]
	v_mfma_f32_16x16x32_bf16 v[118:121], v[174:177], v[190:193], v[118:121]
	v_mfma_f32_16x16x32_bf16 v[114:117], v[182:185], v[190:193], v[114:117]
	v_mfma_f32_16x16x32_bf16 v[102:105], v[174:177], v[198:201], v[102:105]
	v_mfma_f32_16x16x32_bf16 v[98:101], v[182:185], v[198:201], v[98:101]
	v_mfma_f32_16x16x32_bf16 v[86:89], v[174:177], v[206:209], v[86:89]
	v_mfma_f32_16x16x32_bf16 v[82:85], v[182:185], v[206:209], v[82:85]
	v_mfma_f32_16x16x32_bf16 v[70:73], v[174:177], v[236:239], v[70:73]
	v_mfma_f32_16x16x32_bf16 v[66:69], v[182:185], v[236:239], v[66:69]
	s_barrier
	s_add_i32 s34, s56, s27
	v_lshl_add_u64 v[224:225], v[224:225], 0, s[96:97]
	s_mov_b32 m0, s34
	ds_read_b128 v[186:189], v157 offset:49152
	ds_read_b128 v[190:193], v157 offset:50176
	ds_read_b128 v[194:197], v157 offset:51200
	ds_read_b128 v[198:201], v157 offset:52224
	ds_read_b128 v[202:205], v157 offset:53248
	ds_read_b128 v[206:209], v157 offset:54272
	ds_read_b128 v[220:223], v157 offset:55296
	ds_read_b128 v[236:239], v157 offset:56320
	global_load_lds_dwordx4 v[224:225], off
	s_add_i32 m0, s34, 0x2000
	s_add_u32 s30, s30, 0x40080
	v_lshl_add_u64 v[224:225], v[230:231], 0, s[96:97]
	s_addc_u32 s31, s31, 0
	s_add_i32 s34, s57, s27
	global_load_lds_dwordx4 v[224:225], off
	v_lshl_add_u64 v[224:225], s[30:31], 0, v[132:133]
	s_mov_b32 m0, s34
	s_nop 0
	global_load_lds_dwordx4 v[224:225], off
	v_lshl_add_u64 v[224:225], s[30:31], 0, v[136:137]
	s_add_i32 m0, s34, 0x2000
	s_nop 0
	global_load_lds_dwordx4 v[224:225], off
	v_lshl_add_u64 v[224:225], v[240:241], 0, s[96:97]
	s_mov_b32 m0, s47
	s_nop 0
	global_load_lds_dwordx4 v[224:225], off
	v_lshl_add_u64 v[224:225], v[242:243], 0, s[96:97]
	s_mov_b32 m0, s48
	s_nop 0
	global_load_lds_dwordx4 v[224:225], off
	s_nop 0
	s_nop 0
	s_waitcnt vmcnt(8)
	s_waitcnt lgkmcnt(0)
	s_barrier
	s_waitcnt lgkmcnt(0)
	v_mfma_f32_16x16x32_bf16 v[62:65], v[142:145], v[186:189], v[62:65]
	v_mfma_f32_16x16x32_bf16 v[58:61], v[162:165], v[186:189], v[58:61]
	v_mfma_f32_16x16x32_bf16 v[46:49], v[142:145], v[194:197], v[46:49]
	v_mfma_f32_16x16x32_bf16 v[42:45], v[162:165], v[194:197], v[42:45]
	v_mfma_f32_16x16x32_bf16 v[30:33], v[142:145], v[202:205], v[30:33]
	v_mfma_f32_16x16x32_bf16 v[26:29], v[162:165], v[202:205], v[26:29]
	v_mfma_f32_16x16x32_bf16 v[14:17], v[142:145], v[220:223], v[14:17]
	v_mfma_f32_16x16x32_bf16 v[10:13], v[162:165], v[220:223], v[10:13]
	v_mfma_f32_16x16x32_bf16 v[62:65], v[158:161], v[190:193], v[62:65]
	v_mfma_f32_16x16x32_bf16 v[58:61], v[166:169], v[190:193], v[58:61]
	v_mfma_f32_16x16x32_bf16 v[46:49], v[158:161], v[198:201], v[46:49]
	v_mfma_f32_16x16x32_bf16 v[42:45], v[166:169], v[198:201], v[42:45]
	v_mfma_f32_16x16x32_bf16 v[30:33], v[158:161], v[206:209], v[30:33]
	v_mfma_f32_16x16x32_bf16 v[26:29], v[166:169], v[206:209], v[26:29]
	v_mfma_f32_16x16x32_bf16 v[14:17], v[158:161], v[236:239], v[14:17]
	v_mfma_f32_16x16x32_bf16 v[10:13], v[166:169], v[236:239], v[10:13]
	v_mfma_f32_16x16x32_bf16 v[54:57], v[170:173], v[186:189], v[54:57]
	v_mfma_f32_16x16x32_bf16 v[50:53], v[178:181], v[186:189], v[50:53]
	v_mfma_f32_16x16x32_bf16 v[38:41], v[170:173], v[194:197], v[38:41]
	v_mfma_f32_16x16x32_bf16 v[34:37], v[178:181], v[194:197], v[34:37]
	v_mfma_f32_16x16x32_bf16 v[22:25], v[170:173], v[202:205], v[22:25]
	v_mfma_f32_16x16x32_bf16 v[18:21], v[178:181], v[202:205], v[18:21]
	v_mfma_f32_16x16x32_bf16 v[6:9], v[170:173], v[220:223], v[6:9]
	v_mfma_f32_16x16x32_bf16 v[2:5], v[178:181], v[220:223], v[2:5]
	v_mfma_f32_16x16x32_bf16 v[54:57], v[174:177], v[190:193], v[54:57]
	v_mfma_f32_16x16x32_bf16 v[50:53], v[182:185], v[190:193], v[50:53]
	v_mfma_f32_16x16x32_bf16 v[38:41], v[174:177], v[198:201], v[38:41]
	v_mfma_f32_16x16x32_bf16 v[34:37], v[182:185], v[198:201], v[34:37]
	v_mfma_f32_16x16x32_bf16 v[22:25], v[174:177], v[206:209], v[22:25]
	v_mfma_f32_16x16x32_bf16 v[18:21], v[182:185], v[206:209], v[18:21]
	v_mfma_f32_16x16x32_bf16 v[6:9], v[174:177], v[236:239], v[6:9]
	v_mfma_f32_16x16x32_bf16 v[2:5], v[182:185], v[236:239], v[2:5]
	s_barrier
	s_add_i32 s55, s55, 2
	s_add_u32 s38, s38, 0x100
	s_addc_u32 s39, s39, 0
	s_add_u32 s28, s28, 0x100
	s_addc_u32 s29, s29, 0
	s_cmp_gt_u32 s55, 13

.LBB0_360:
	v_add_u32_e32 v146, 0x10000, v155
	ds_read_b128 v[142:145], v146
	ds_read_b128 v[168:171], v146 offset:1024
	ds_read_b128 v[172:175], v146 offset:2048
	ds_read_b128 v[176:179], v146 offset:3072
	v_add_u32_e32 v146, 0x14000, v155
	ds_read_b128 v[180:183], v146
	ds_read_b128 v[184:187], v146 offset:1024
	ds_read_b128 v[188:191], v146 offset:2048
	ds_read_b128 v[192:195], v146 offset:3072
	ds_read_b128 v[196:199], v157
	ds_read_b128 v[200:203], v157 offset:1024
	ds_read_b128 v[204:207], v157 offset:2048
	ds_read_b128 v[220:223], v157 offset:3072
	ds_read_b128 v[236:239], v157 offset:4096
	ds_read_b128 v[240:243], v157 offset:5120
	ds_read_b128 v[244:247], v157 offset:6144
	ds_read_b128 v[248:251], v157 offset:7168
	s_add_i32 s55, s38, 1
	s_mul_i32 s6, s55, s54
	s_mul_hi_u32 s7, s55, s98
	s_add_i32 s7, s7, s6
	s_mul_i32 s6, s55, s98
	v_readlane_b32 s24, v254, 47
	v_readlane_b32 s25, v254, 48
	s_add_u32 s24, s6, s24
	s_addc_u32 s25, s7, s47
	v_mov_b64_e32 v[2:3], 0x580
	v_cmp_lt_i64_e64 s[6:7], s[24:25], v[2:3]
	v_mov_b64_e32 v[2:3], 0x57f
	v_cmp_gt_i64_e32 vcc, s[24:25], v[2:3]
	s_cbranch_vccnz .LBB0_362
	s_cmpk_lg_i32 s98, 0x100
	s_cbranch_scc1 .Lsw_dec_gen
	s_add_i32 s20, s29, 4
	s_mov_b32 s22, s28
	s_branch .LBB0_362

.LBB0_362:
	s_ashr_i32 s23, s22, 31
	s_lshl_b64 s[24:25], s[22:23], 19
	s_add_u32 s24, s80, s24
	s_addc_u32 s25, s81, s25
	s_and_b64 s[26:27], s[6:7], exec
	s_cselect_b32 s23, s25, s35
	s_cselect_b32 s39, s24, s34
	s_ashr_i32 s21, s20, 31
	s_lshl_b64 s[26:27], s[20:21], 19
	s_add_u32 s26, s45, s26
	s_addc_u32 s27, s46, s27
	s_and_b64 s[36:37], s[6:7], exec
	s_cselect_b32 s21, s27, s31
	s_cselect_b32 s40, s26, s30
	s_add_u32 s41, s30, 0x100
	s_addc_u32 s43, s31, 0
	s_add_u32 s30, s34, 0x40080
	s_addc_u32 s31, s35, 0
	s_mov_b32 s56, -2
	s_add_u32 s34, s30, 0xfffc0080
	s_addc_u32 s35, s31, -1
	s_add_i32 s57, 0, 0x10000
	s_cmp_eq_u32 s56, 12
	s_cselect_b32 s37, s23, s35
	s_cselect_b32 s36, s39, s34
	s_cselect_b32 s35, s21, s43
	s_cselect_b32 s34, s40, s41
	s_add_i32 s60, 0, 0x14000
	v_lshl_add_u64 v[146:147], s[30:31], 0, v[140:141]
	s_add_i32 m0, s48, 0xc000
	global_load_lds_dwordx4 v[146:147], off
	v_lshl_add_u64 v[146:147], s[30:31], 0, v[138:139]
	s_add_i32 m0, s48, 0xe000
	s_nop 0
	global_load_lds_dwordx4 v[146:147], off
	s_nop 0
	s_nop 0
	s_nop 0
	s_nop 0
	s_nop 0
	s_nop 0
	s_nop 0
	s_nop 0
	s_nop 0
	s_nop 0
	s_nop 0
	s_nop 0
	s_nop 0
	s_nop 0
	s_nop 0
	s_nop 0
	s_nop 0
	s_nop 0
	s_nop 0
	s_waitcnt vmcnt(8)
	s_waitcnt lgkmcnt(0)
	s_barrier
	s_waitcnt lgkmcnt(0)
	v_mfma_f32_16x16x32_bf16 v[126:129], v[142:145], v[196:199], 0
	v_mfma_f32_16x16x32_bf16 v[118:121], v[172:175], v[196:199], 0
	v_mfma_f32_16x16x32_bf16 v[110:113], v[142:145], v[204:207], 0
	v_mfma_f32_16x16x32_bf16 v[102:105], v[172:175], v[204:207], 0
	v_mfma_f32_16x16x32_bf16 v[94:97], v[142:145], v[236:239], 0
	v_mfma_f32_16x16x32_bf16 v[86:89], v[172:175], v[236:239], 0
	v_mfma_f32_16x16x32_bf16 v[78:81], v[142:145], v[244:247], 0
	v_mfma_f32_16x16x32_bf16 v[70:73], v[172:175], v[244:247], 0
	v_mfma_f32_16x16x32_bf16 v[126:129], v[168:171], v[200:203], v[126:129]
	v_mfma_f32_16x16x32_bf16 v[118:121], v[176:179], v[200:203], v[118:121]
	v_mfma_f32_16x16x32_bf16 v[110:113], v[168:171], v[220:223], v[110:113]
	v_mfma_f32_16x16x32_bf16 v[102:105], v[176:179], v[220:223], v[102:105]
	v_mfma_f32_16x16x32_bf16 v[94:97], v[168:171], v[240:243], v[94:97]
	v_mfma_f32_16x16x32_bf16 v[86:89], v[176:179], v[240:243], v[86:89]
	v_mfma_f32_16x16x32_bf16 v[78:81], v[168:171], v[248:251], v[78:81]
	v_mfma_f32_16x16x32_bf16 v[70:73], v[176:179], v[248:251], v[70:73]
	v_mfma_f32_16x16x32_bf16 v[122:125], v[180:183], v[196:199], 0
	v_mfma_f32_16x16x32_bf16 v[114:117], v[188:191], v[196:199], 0
	v_mfma_f32_16x16x32_bf16 v[106:109], v[180:183], v[204:207], 0
	v_mfma_f32_16x16x32_bf16 v[98:101], v[188:191], v[204:207], 0
	v_mfma_f32_16x16x32_bf16 v[90:93], v[180:183], v[236:239], 0
	v_mfma_f32_16x16x32_bf16 v[82:85], v[188:191], v[236:239], 0
	v_mfma_f32_16x16x32_bf16 v[74:77], v[180:183], v[244:247], 0
	v_mfma_f32_16x16x32_bf16 v[66:69], v[188:191], v[244:247], 0
	v_mfma_f32_16x16x32_bf16 v[122:125], v[184:187], v[200:203], v[122:125]
	v_mfma_f32_16x16x32_bf16 v[114:117], v[192:195], v[200:203], v[114:117]
	v_mfma_f32_16x16x32_bf16 v[106:109], v[184:187], v[220:223], v[106:109]
	v_mfma_f32_16x16x32_bf16 v[98:101], v[192:195], v[220:223], v[98:101]
	v_mfma_f32_16x16x32_bf16 v[90:93], v[184:187], v[240:243], v[90:93]
	v_mfma_f32_16x16x32_bf16 v[82:85], v[192:195], v[240:243], v[82:85]
	v_mfma_f32_16x16x32_bf16 v[74:77], v[184:187], v[248:251], v[74:77]
	v_mfma_f32_16x16x32_bf16 v[66:69], v[192:195], v[248:251], v[66:69]
	s_barrier
	s_add_i32 s57, s57, s44
	v_lshl_add_u64 v[146:147], s[34:35], 0, v[134:135]
	s_mov_b32 m0, s57
	ds_read_b128 v[196:199], v157 offset:16384
	ds_read_b128 v[200:203], v157 offset:17408
	ds_read_b128 v[204:207], v157 offset:18432
	ds_read_b128 v[220:223], v157 offset:19456
	ds_read_b128 v[236:239], v157 offset:20480
	ds_read_b128 v[240:243], v157 offset:21504
	ds_read_b128 v[244:247], v157 offset:22528
	ds_read_b128 v[248:251], v157 offset:23552
	global_load_lds_dwordx4 v[146:147], off
	s_add_i32 m0, s57, 0x2000
	s_add_u32 s58, s34, 0x40000
	v_lshl_add_u64 v[208:209], s[34:35], 0, v[130:131]
	s_addc_u32 s59, s35, 0
	s_add_i32 s57, s60, s44
	global_load_lds_dwordx4 v[208:209], off
	v_lshl_add_u64 v[224:225], s[58:59], 0, v[134:135]
	s_mov_b32 m0, s57
	v_lshl_add_u64 v[230:231], s[36:37], 0, v[132:133]
	global_load_lds_dwordx4 v[224:225], off
	v_lshl_add_u64 v[224:225], s[58:59], 0, v[130:131]
	s_add_i32 m0, s57, 0x2000
	s_nop 0
	global_load_lds_dwordx4 v[224:225], off
	v_lshl_add_u64 v[224:225], s[36:37], 0, v[136:137]
	s_mov_b32 m0, s48
	s_nop 0
	global_load_lds_dwordx4 v[224:225], off
	s_mov_b32 m0, s49
	s_nop 0
	global_load_lds_dwordx4 v[230:231], off
	s_nop 0
	s_nop 0
	s_nop 0
	s_waitcnt vmcnt(8)
	s_waitcnt lgkmcnt(0)
	s_barrier
	s_waitcnt lgkmcnt(0)
	v_mfma_f32_16x16x32_bf16 v[62:65], v[142:145], v[196:199], 0
	v_mfma_f32_16x16x32_bf16 v[54:57], v[172:175], v[196:199], 0
	v_mfma_f32_16x16x32_bf16 v[46:49], v[142:145], v[204:207], 0
	v_mfma_f32_16x16x32_bf16 v[38:41], v[172:175], v[204:207], 0
	v_mfma_f32_16x16x32_bf16 v[30:33], v[142:145], v[236:239], 0
	v_mfma_f32_16x16x32_bf16 v[22:25], v[172:175], v[236:239], 0
	v_mfma_f32_16x16x32_bf16 v[14:17], v[142:145], v[244:247], 0
	v_mfma_f32_16x16x32_bf16 v[6:9], v[172:175], v[244:247], 0
	v_mfma_f32_16x16x32_bf16 v[62:65], v[168:171], v[200:203], v[62:65]
	v_mfma_f32_16x16x32_bf16 v[54:57], v[176:179], v[200:203], v[54:57]
	v_mfma_f32_16x16x32_bf16 v[46:49], v[168:171], v[220:223], v[46:49]
	v_mfma_f32_16x16x32_bf16 v[38:41], v[176:179], v[220:223], v[38:41]
	v_mfma_f32_16x16x32_bf16 v[30:33], v[168:171], v[240:243], v[30:33]
	v_mfma_f32_16x16x32_bf16 v[22:25], v[176:179], v[240:243], v[22:25]
	v_mfma_f32_16x16x32_bf16 v[14:17], v[168:171], v[248:251], v[14:17]
	v_mfma_f32_16x16x32_bf16 v[6:9], v[176:179], v[248:251], v[6:9]
	v_mfma_f32_16x16x32_bf16 v[58:61], v[180:183], v[196:199], 0
	v_mfma_f32_16x16x32_bf16 v[50:53], v[188:191], v[196:199], 0
	v_mfma_f32_16x16x32_bf16 v[42:45], v[180:183], v[204:207], 0
	v_mfma_f32_16x16x32_bf16 v[34:37], v[188:191], v[204:207], 0
	v_mfma_f32_16x16x32_bf16 v[26:29], v[180:183], v[236:239], 0
	v_mfma_f32_16x16x32_bf16 v[18:21], v[188:191], v[236:239], 0
	v_mfma_f32_16x16x32_bf16 v[10:13], v[180:183], v[244:247], 0
	v_mfma_f32_16x16x32_bf16 v[2:5], v[188:191], v[244:247], 0
	v_mfma_f32_16x16x32_bf16 v[58:61], v[184:187], v[200:203], v[58:61]
	v_mfma_f32_16x16x32_bf16 v[50:53], v[192:195], v[200:203], v[50:53]
	v_mfma_f32_16x16x32_bf16 v[42:45], v[184:187], v[220:223], v[42:45]
	v_mfma_f32_16x16x32_bf16 v[34:37], v[192:195], v[220:223], v[34:37]
	v_mfma_f32_16x16x32_bf16 v[26:29], v[184:187], v[240:243], v[26:29]
	v_mfma_f32_16x16x32_bf16 v[18:21], v[192:195], v[240:243], v[18:21]
	v_mfma_f32_16x16x32_bf16 v[10:13], v[184:187], v[248:251], v[10:13]
	v_mfma_f32_16x16x32_bf16 v[2:5], v[192:195], v[248:251], v[2:5]
	s_barrier
	s_add_i32 s57, 0, 0x18000
	v_add_u32_e32 v164, s57, v155
	s_add_i32 s58, 0, 0x1c000
	ds_read_b128 v[142:145], v164
	ds_read_b128 v[168:171], v164 offset:1024
	ds_read_b128 v[172:175], v164 offset:2048
	ds_read_b128 v[176:179], v164 offset:3072
	v_add_u32_e32 v164, s58, v155
	ds_read_b128 v[180:183], v164
	ds_read_b128 v[184:187], v164 offset:1024
	ds_read_b128 v[188:191], v164 offset:2048
	ds_read_b128 v[192:195], v164 offset:3072
	s_add_u32 s36, s36, 0x40000
	s_addc_u32 s37, s37, 0
	s_mov_b32 m0, s50
	v_lshl_add_u64 v[252:253], s[36:37], 0, v[136:137]
	ds_read_b128 v[196:199], v157 offset:32768
	ds_read_b128 v[200:203], v157 offset:33792
	ds_read_b128 v[204:207], v157 offset:34816
	ds_read_b128 v[220:223], v157 offset:35840
	ds_read_b128 v[236:239], v157 offset:36864
	ds_read_b128 v[240:243], v157 offset:37888
	ds_read_b128 v[244:247], v157 offset:38912
	ds_read_b128 v[248:251], v157 offset:39936
	global_load_lds_dwordx4 v[252:253], off
	v_lshl_add_u64 v[252:253], s[36:37], 0, v[132:133]
	s_mov_b32 m0, s51
	s_nop 0
	global_load_lds_dwordx4 v[252:253], off
	s_nop 0
	s_nop 0
	s_nop 0
	s_nop 0
	s_nop 0
	s_nop 0
	s_nop 0
	s_waitcnt vmcnt(8)
	s_waitcnt lgkmcnt(0)
	s_barrier
	s_waitcnt lgkmcnt(0)
	v_mfma_f32_16x16x32_bf16 v[126:129], v[142:145], v[196:199], v[126:129]
	v_mfma_f32_16x16x32_bf16 v[118:121], v[172:175], v[196:199], v[118:121]
	v_mfma_f32_16x16x32_bf16 v[110:113], v[142:145], v[204:207], v[110:113]
	v_mfma_f32_16x16x32_bf16 v[102:105], v[172:175], v[204:207], v[102:105]
	v_mfma_f32_16x16x32_bf16 v[94:97], v[142:145], v[236:239], v[94:97]
	v_mfma_f32_16x16x32_bf16 v[86:89], v[172:175], v[236:239], v[86:89]
	v_mfma_f32_16x16x32_bf16 v[78:81], v[142:145], v[244:247], v[78:81]
	v_mfma_f32_16x16x32_bf16 v[70:73], v[172:175], v[244:247], v[70:73]
	v_mfma_f32_16x16x32_bf16 v[126:129], v[168:171], v[200:203], v[126:129]
	v_mfma_f32_16x16x32_bf16 v[118:121], v[176:179], v[200:203], v[118:121]
	v_mfma_f32_16x16x32_bf16 v[110:113], v[168:171], v[220:223], v[110:113]
	v_mfma_f32_16x16x32_bf16 v[102:105], v[176:179], v[220:223], v[102:105]
	v_mfma_f32_16x16x32_bf16 v[94:97], v[168:171], v[240:243], v[94:97]
	v_mfma_f32_16x16x32_bf16 v[86:89], v[176:179], v[240:243], v[86:89]
	v_mfma_f32_16x16x32_bf16 v[78:81], v[168:171], v[248:251], v[78:81]
	v_mfma_f32_16x16x32_bf16 v[70:73], v[176:179], v[248:251], v[70:73]
	v_mfma_f32_16x16x32_bf16 v[122:125], v[180:183], v[196:199], v[122:125]
	v_mfma_f32_16x16x32_bf16 v[114:117], v[188:191], v[196:199], v[114:117]
	v_mfma_f32_16x16x32_bf16 v[106:109], v[180:183], v[204:207], v[106:109]
	v_mfma_f32_16x16x32_bf16 v[98:101], v[188:191], v[204:207], v[98:101]
	v_mfma_f32_16x16x32_bf16 v[90:93], v[180:183], v[236:239], v[90:93]
	v_mfma_f32_16x16x32_bf16 v[82:85], v[188:191], v[236:239], v[82:85]
	v_mfma_f32_16x16x32_bf16 v[74:77], v[180:183], v[244:247], v[74:77]
	v_mfma_f32_16x16x32_bf16 v[66:69], v[188:191], v[244:247], v[66:69]
	v_mfma_f32_16x16x32_bf16 v[122:125], v[184:187], v[200:203], v[122:125]
	v_mfma_f32_16x16x32_bf16 v[114:117], v[192:195], v[200:203], v[114:117]
	v_mfma_f32_16x16x32_bf16 v[106:109], v[184:187], v[220:223], v[106:109]
	v_mfma_f32_16x16x32_bf16 v[98:101], v[192:195], v[220:223], v[98:101]
	v_mfma_f32_16x16x32_bf16 v[90:93], v[184:187], v[240:243], v[90:93]
	v_mfma_f32_16x16x32_bf16 v[82:85], v[192:195], v[240:243], v[82:85]
	v_mfma_f32_16x16x32_bf16 v[74:77], v[184:187], v[248:251], v[74:77]
	v_mfma_f32_16x16x32_bf16 v[66:69], v[192:195], v[248:251], v[66:69]
	s_barrier
	s_add_i32 s36, s57, s44
	v_lshl_add_u64 v[146:147], v[146:147], 0, s[96:97]
	s_mov_b32 m0, s36
	ds_read_b128 v[196:199], v157 offset:49152
	ds_read_b128 v[200:203], v157 offset:50176
	ds_read_b128 v[204:207], v157 offset:51200
	ds_read_b128 v[220:223], v157 offset:52224
	ds_read_b128 v[236:239], v157 offset:53248
	ds_read_b128 v[240:243], v157 offset:54272
	ds_read_b128 v[244:247], v157 offset:55296
	ds_read_b128 v[248:251], v157 offset:56320
	global_load_lds_dwordx4 v[146:147], off
	s_add_i32 m0, s36, 0x2000
	s_add_u32 s34, s34, 0x40080
	v_lshl_add_u64 v[146:147], v[208:209], 0, s[96:97]
	s_addc_u32 s35, s35, 0
	s_add_i32 s36, s58, s44
	global_load_lds_dwordx4 v[146:147], off
	v_lshl_add_u64 v[146:147], s[34:35], 0, v[134:135]
	s_mov_b32 m0, s36
	s_nop 0
	global_load_lds_dwordx4 v[146:147], off
	v_lshl_add_u64 v[146:147], s[34:35], 0, v[130:131]
	s_add_i32 m0, s36, 0x2000
	s_nop 0
	global_load_lds_dwordx4 v[146:147], off
	v_lshl_add_u64 v[146:147], v[224:225], 0, s[96:97]
	s_mov_b32 m0, s52
	s_nop 0
	global_load_lds_dwordx4 v[146:147], off
	v_lshl_add_u64 v[146:147], v[230:231], 0, s[96:97]
	s_mov_b32 m0, s53
	s_nop 0
	global_load_lds_dwordx4 v[146:147], off
	s_nop 0
	s_nop 0
	s_waitcnt vmcnt(8)
	s_waitcnt lgkmcnt(0)
	s_barrier
	s_waitcnt lgkmcnt(0)
	v_mfma_f32_16x16x32_bf16 v[62:65], v[142:145], v[196:199], v[62:65]
	v_mfma_f32_16x16x32_bf16 v[54:57], v[172:175], v[196:199], v[54:57]
	v_mfma_f32_16x16x32_bf16 v[46:49], v[142:145], v[204:207], v[46:49]
	v_mfma_f32_16x16x32_bf16 v[38:41], v[172:175], v[204:207], v[38:41]
	v_mfma_f32_16x16x32_bf16 v[30:33], v[142:145], v[236:239], v[30:33]
	v_mfma_f32_16x16x32_bf16 v[22:25], v[172:175], v[236:239], v[22:25]
	v_mfma_f32_16x16x32_bf16 v[14:17], v[142:145], v[244:247], v[14:17]
	v_mfma_f32_16x16x32_bf16 v[6:9], v[172:175], v[244:247], v[6:9]
	v_mfma_f32_16x16x32_bf16 v[62:65], v[168:171], v[200:203], v[62:65]
	v_mfma_f32_16x16x32_bf16 v[54:57], v[176:179], v[200:203], v[54:57]
	v_mfma_f32_16x16x32_bf16 v[46:49], v[168:171], v[220:223], v[46:49]
	v_mfma_f32_16x16x32_bf16 v[38:41], v[176:179], v[220:223], v[38:41]
	v_mfma_f32_16x16x32_bf16 v[30:33], v[168:171], v[240:243], v[30:33]
	v_mfma_f32_16x16x32_bf16 v[22:25], v[176:179], v[240:243], v[22:25]
	v_mfma_f32_16x16x32_bf16 v[14:17], v[168:171], v[248:251], v[14:17]
	v_mfma_f32_16x16x32_bf16 v[6:9], v[176:179], v[248:251], v[6:9]
	v_mfma_f32_16x16x32_bf16 v[58:61], v[180:183], v[196:199], v[58:61]
	v_mfma_f32_16x16x32_bf16 v[50:53], v[188:191], v[196:199], v[50:53]
	v_mfma_f32_16x16x32_bf16 v[42:45], v[180:183], v[204:207], v[42:45]
	v_mfma_f32_16x16x32_bf16 v[34:37], v[188:191], v[204:207], v[34:37]
	v_mfma_f32_16x16x32_bf16 v[26:29], v[180:183], v[236:239], v[26:29]
	v_mfma_f32_16x16x32_bf16 v[18:21], v[188:191], v[236:239], v[18:21]
	v_mfma_f32_16x16x32_bf16 v[10:13], v[180:183], v[244:247], v[10:13]
	v_mfma_f32_16x16x32_bf16 v[2:5], v[188:191], v[244:247], v[2:5]
	v_mfma_f32_16x16x32_bf16 v[58:61], v[184:187], v[200:203], v[58:61]
	v_mfma_f32_16x16x32_bf16 v[50:53], v[192:195], v[200:203], v[50:53]
	v_mfma_f32_16x16x32_bf16 v[42:45], v[184:187], v[220:223], v[42:45]
	v_mfma_f32_16x16x32_bf16 v[34:37], v[192:195], v[220:223], v[34:37]
	v_mfma_f32_16x16x32_bf16 v[26:29], v[184:187], v[240:243], v[26:29]
	v_mfma_f32_16x16x32_bf16 v[18:21], v[192:195], v[240:243], v[18:21]
	v_mfma_f32_16x16x32_bf16 v[10:13], v[184:187], v[248:251], v[10:13]
	v_mfma_f32_16x16x32_bf16 v[2:5], v[192:195], v[248:251], v[2:5]
	s_barrier
	s_add_i32 s56, s56, 2
	s_add_u32 s41, s41, 0x100
	s_addc_u32 s43, s43, 0
	s_add_u32 s30, s30, 0x100
	s_addc_u32 s31, s31, 0
	s_cmp_gt_u32 s56, 13

.LBB0_637:
	v_add_u32_e32 v150, 0x10000, v159
	ds_read_b128 v[164:167], v150
	ds_read_b128 v[168:171], v150 offset:1024
	ds_read_b128 v[172:175], v150 offset:2048
	ds_read_b128 v[176:179], v150 offset:3072
	v_add_u32_e32 v150, 0x14000, v159
	ds_read_b128 v[180:183], v150
	ds_read_b128 v[184:187], v150 offset:1024
	ds_read_b128 v[188:191], v150 offset:2048
	ds_read_b128 v[192:195], v150 offset:3072
	ds_read_b128 v[196:199], v162
	ds_read_b128 v[200:203], v162 offset:1024
	ds_read_b128 v[204:207], v162 offset:2048
	ds_read_b128 v[220:223], v162 offset:3072
	ds_read_b128 v[236:239], v162 offset:4096
	ds_read_b128 v[240:243], v162 offset:5120
	ds_read_b128 v[244:247], v162 offset:6144
	ds_read_b128 v[248:251], v162 offset:7168
	s_add_i32 s39, s39, 1
	s_mul_i32 s4, s39, s38
	s_mul_hi_u32 s5, s39, s98
	s_add_i32 s5, s5, s4
	s_mul_i32 s4, s39, s98
	s_add_u32 s14, s4, s52
	s_addc_u32 s15, s5, s29
	v_cmp_gt_i64_e32 vcc, s[14:15], v[212:213]
	v_cmp_lt_i64_e64 s[4:5], s[14:15], v[210:211]
	s_cbranch_vccnz .LBB0_639
	s_cmpk_lg_i32 s98, 0x100
	s_cbranch_scc1 .Lci_dec_gen
	s_add_i32 s10, s40, 4
	s_mov_b32 s12, s18
	s_branch .LBB0_639

.LBB0_639:
	s_ashr_i32 s13, s12, 31
	s_lshl_b64 s[14:15], s[12:13], 19
	s_add_u32 s14, s80, s14
	s_addc_u32 s15, s81, s15
	s_and_b64 s[16:17], s[4:5], exec
	s_cselect_b32 s13, s15, s23
	s_cselect_b32 s19, s14, s22
	s_ashr_i32 s11, s10, 31
	s_lshl_b64 s[16:17], s[10:11], 19
	s_add_u32 s16, s26, s16
	s_addc_u32 s17, s27, s17
	s_and_b64 s[24:25], s[4:5], exec
	s_cselect_b32 s11, s17, s21
	s_cselect_b32 s41, s16, s20
	s_add_u32 s43, s20, 0x100
	s_addc_u32 s44, s21, 0
	s_add_u32 s20, s22, 0x40080
	s_addc_u32 s21, s23, 0
	s_mov_b32 s45, -2
	s_add_u32 s22, s20, 0xfffc0080
	s_addc_u32 s23, s21, -1
	s_add_i32 s46, 0, 0x10000
	s_cmp_eq_u32 s45, 12
	s_cselect_b32 s25, s13, s23
	s_cselect_b32 s24, s19, s22
	s_cselect_b32 s23, s11, s44
	s_cselect_b32 s22, s41, s43
	s_add_i32 s48, 0, 0x14000
	v_lshl_add_u64 v[150:151], s[20:21], 0, v[140:141]
	s_add_i32 m0, s30, 0xc000
	global_load_lds_dwordx4 v[150:151], off
	v_lshl_add_u64 v[150:151], s[20:21], 0, v[138:139]
	s_add_i32 m0, s30, 0xe000
	s_nop 0
	global_load_lds_dwordx4 v[150:151], off
	s_nop 0
	s_nop 0
	s_nop 0
	s_nop 0
	s_nop 0
	s_nop 0
	s_nop 0
	s_nop 0
	s_nop 0
	s_nop 0
	s_nop 0
	s_nop 0
	s_nop 0
	s_nop 0
	s_nop 0
	s_nop 0
	s_nop 0
	s_nop 0
	s_nop 0
	s_nop 0
	s_nop 0
	s_nop 0
	s_waitcnt vmcnt(8)
	s_waitcnt lgkmcnt(0)
	s_barrier
	s_waitcnt lgkmcnt(0)
	v_mfma_f32_16x16x32_bf16 v[126:129], v[164:167], v[196:199], 0
	v_mfma_f32_16x16x32_bf16 v[122:125], v[172:175], v[196:199], 0
	v_mfma_f32_16x16x32_bf16 v[118:121], v[164:167], v[204:207], 0
	v_mfma_f32_16x16x32_bf16 v[114:117], v[172:175], v[204:207], 0
	v_mfma_f32_16x16x32_bf16 v[110:113], v[164:167], v[236:239], 0
	v_mfma_f32_16x16x32_bf16 v[106:109], v[172:175], v[236:239], 0
	v_mfma_f32_16x16x32_bf16 v[102:105], v[164:167], v[244:247], 0
	v_mfma_f32_16x16x32_bf16 v[98:101], v[172:175], v[244:247], 0
	v_mfma_f32_16x16x32_bf16 v[126:129], v[168:171], v[200:203], v[126:129]
	v_mfma_f32_16x16x32_bf16 v[122:125], v[176:179], v[200:203], v[122:125]
	v_mfma_f32_16x16x32_bf16 v[118:121], v[168:171], v[220:223], v[118:121]
	v_mfma_f32_16x16x32_bf16 v[114:117], v[176:179], v[220:223], v[114:117]
	v_mfma_f32_16x16x32_bf16 v[110:113], v[168:171], v[240:243], v[110:113]
	v_mfma_f32_16x16x32_bf16 v[106:109], v[176:179], v[240:243], v[106:109]
	v_mfma_f32_16x16x32_bf16 v[102:105], v[168:171], v[248:251], v[102:105]
	v_mfma_f32_16x16x32_bf16 v[98:101], v[176:179], v[248:251], v[98:101]
	v_mfma_f32_16x16x32_bf16 v[94:97], v[180:183], v[196:199], 0
	v_mfma_f32_16x16x32_bf16 v[90:93], v[188:191], v[196:199], 0
	v_mfma_f32_16x16x32_bf16 v[86:89], v[180:183], v[204:207], 0
	v_mfma_f32_16x16x32_bf16 v[82:85], v[188:191], v[204:207], 0
	v_mfma_f32_16x16x32_bf16 v[78:81], v[180:183], v[236:239], 0
	v_mfma_f32_16x16x32_bf16 v[74:77], v[188:191], v[236:239], 0
	v_mfma_f32_16x16x32_bf16 v[70:73], v[180:183], v[244:247], 0
	v_mfma_f32_16x16x32_bf16 v[66:69], v[188:191], v[244:247], 0
	v_mfma_f32_16x16x32_bf16 v[94:97], v[184:187], v[200:203], v[94:97]
	v_mfma_f32_16x16x32_bf16 v[90:93], v[192:195], v[200:203], v[90:93]
	v_mfma_f32_16x16x32_bf16 v[86:89], v[184:187], v[220:223], v[86:89]
	v_mfma_f32_16x16x32_bf16 v[82:85], v[192:195], v[220:223], v[82:85]
	v_mfma_f32_16x16x32_bf16 v[78:81], v[184:187], v[240:243], v[78:81]
	v_mfma_f32_16x16x32_bf16 v[74:77], v[192:195], v[240:243], v[74:77]
	v_mfma_f32_16x16x32_bf16 v[70:73], v[184:187], v[248:251], v[70:73]
	v_mfma_f32_16x16x32_bf16 v[66:69], v[192:195], v[248:251], v[66:69]
	s_barrier
	s_add_i32 s46, s46, s28
	v_lshl_add_u64 v[150:151], s[22:23], 0, v[134:135]
	s_mov_b32 m0, s46
	ds_read_b128 v[196:199], v162 offset:16384
	ds_read_b128 v[200:203], v162 offset:17408
	ds_read_b128 v[204:207], v162 offset:18432
	ds_read_b128 v[220:223], v162 offset:19456
	ds_read_b128 v[236:239], v162 offset:20480
	ds_read_b128 v[240:243], v162 offset:21504
	ds_read_b128 v[244:247], v162 offset:22528
	ds_read_b128 v[248:251], v162 offset:23552
	global_load_lds_dwordx4 v[150:151], off
	s_add_i32 m0, s46, 0x2000
	s_add_u32 s46, s22, 0x40000
	v_lshl_add_u64 v[208:209], s[22:23], 0, v[130:131]
	s_addc_u32 s47, s23, 0
	s_add_i32 s48, s48, s28
	global_load_lds_dwordx4 v[208:209], off
	v_lshl_add_u64 v[224:225], s[46:47], 0, v[134:135]
	s_mov_b32 m0, s48
	v_lshl_add_u64 v[252:253], s[24:25], 0, v[132:133]
	global_load_lds_dwordx4 v[224:225], off
	v_lshl_add_u64 v[224:225], s[46:47], 0, v[130:131]
	s_add_i32 m0, s48, 0x2000
	s_nop 0
	global_load_lds_dwordx4 v[224:225], off
	v_lshl_add_u64 v[224:225], s[24:25], 0, v[136:137]
	s_mov_b32 m0, s30
	s_nop 0
	global_load_lds_dwordx4 v[224:225], off
	s_mov_b32 m0, s31
	s_nop 0
	global_load_lds_dwordx4 v[252:253], off
	s_nop 0
	s_nop 0
	s_nop 0
	s_waitcnt vmcnt(8)
	s_waitcnt lgkmcnt(0)
	s_barrier
	s_waitcnt lgkmcnt(0)
	v_mfma_f32_16x16x32_bf16 v[62:65], v[164:167], v[196:199], 0
	v_mfma_f32_16x16x32_bf16 v[58:61], v[172:175], v[196:199], 0
	v_mfma_f32_16x16x32_bf16 v[54:57], v[164:167], v[204:207], 0
	v_mfma_f32_16x16x32_bf16 v[50:53], v[172:175], v[204:207], 0
	v_mfma_f32_16x16x32_bf16 v[46:49], v[164:167], v[236:239], 0
	v_mfma_f32_16x16x32_bf16 v[42:45], v[172:175], v[236:239], 0
	v_mfma_f32_16x16x32_bf16 v[38:41], v[164:167], v[244:247], 0
	v_mfma_f32_16x16x32_bf16 v[34:37], v[172:175], v[244:247], 0
	v_mfma_f32_16x16x32_bf16 v[62:65], v[168:171], v[200:203], v[62:65]
	v_mfma_f32_16x16x32_bf16 v[58:61], v[176:179], v[200:203], v[58:61]
	v_mfma_f32_16x16x32_bf16 v[54:57], v[168:171], v[220:223], v[54:57]
	v_mfma_f32_16x16x32_bf16 v[50:53], v[176:179], v[220:223], v[50:53]
	v_mfma_f32_16x16x32_bf16 v[46:49], v[168:171], v[240:243], v[46:49]
	v_mfma_f32_16x16x32_bf16 v[42:45], v[176:179], v[240:243], v[42:45]
	v_mfma_f32_16x16x32_bf16 v[38:41], v[168:171], v[248:251], v[38:41]
	v_mfma_f32_16x16x32_bf16 v[34:37], v[176:179], v[248:251], v[34:37]
	v_mfma_f32_16x16x32_bf16 v[30:33], v[180:183], v[196:199], 0
	v_mfma_f32_16x16x32_bf16 v[26:29], v[188:191], v[196:199], 0
	v_mfma_f32_16x16x32_bf16 v[22:25], v[180:183], v[204:207], 0
	v_mfma_f32_16x16x32_bf16 v[18:21], v[188:191], v[204:207], 0
	v_mfma_f32_16x16x32_bf16 v[14:17], v[180:183], v[236:239], 0
	v_mfma_f32_16x16x32_bf16 v[10:13], v[188:191], v[236:239], 0
	v_mfma_f32_16x16x32_bf16 v[6:9], v[180:183], v[244:247], 0
	v_mfma_f32_16x16x32_bf16 v[2:5], v[188:191], v[244:247], 0
	v_mfma_f32_16x16x32_bf16 v[30:33], v[184:187], v[200:203], v[30:33]
	v_mfma_f32_16x16x32_bf16 v[26:29], v[192:195], v[200:203], v[26:29]
	v_mfma_f32_16x16x32_bf16 v[22:25], v[184:187], v[220:223], v[22:25]
	v_mfma_f32_16x16x32_bf16 v[18:21], v[192:195], v[220:223], v[18:21]
	v_mfma_f32_16x16x32_bf16 v[14:17], v[184:187], v[240:243], v[14:17]
	v_mfma_f32_16x16x32_bf16 v[10:13], v[192:195], v[240:243], v[10:13]
	v_mfma_f32_16x16x32_bf16 v[6:9], v[184:187], v[248:251], v[6:9]
	v_mfma_f32_16x16x32_bf16 v[2:5], v[192:195], v[248:251], v[2:5]
	s_barrier
	s_add_i32 s46, 0, 0x18000
	v_add_u32_e32 v163, s46, v159
	s_add_i32 s47, 0, 0x1c000
	ds_read_b128 v[164:167], v163
	ds_read_b128 v[168:171], v163 offset:1024
	ds_read_b128 v[172:175], v163 offset:2048
	ds_read_b128 v[176:179], v163 offset:3072
	v_add_u32_e32 v163, s47, v159
	ds_read_b128 v[180:183], v163
	ds_read_b128 v[184:187], v163 offset:1024
	ds_read_b128 v[188:191], v163 offset:2048
	ds_read_b128 v[192:195], v163 offset:3072
	s_add_u32 s24, s24, 0x40000
	s_addc_u32 s25, s25, 0
	s_mov_b32 m0, s34
	v_lshl_add_u64 v[230:231], s[24:25], 0, v[136:137]
	ds_read_b128 v[196:199], v162 offset:32768
	ds_read_b128 v[200:203], v162 offset:33792
	ds_read_b128 v[204:207], v162 offset:34816
	ds_read_b128 v[220:223], v162 offset:35840
	ds_read_b128 v[236:239], v162 offset:36864
	ds_read_b128 v[240:243], v162 offset:37888
	ds_read_b128 v[244:247], v162 offset:38912
	ds_read_b128 v[248:251], v162 offset:39936
	global_load_lds_dwordx4 v[230:231], off
	v_lshl_add_u64 v[230:231], s[24:25], 0, v[132:133]
	s_mov_b32 m0, s35
	s_nop 0
	global_load_lds_dwordx4 v[230:231], off
	s_nop 0
	s_nop 0
	s_nop 0
	s_nop 0
	s_nop 0
	s_nop 0
	s_nop 0
	s_waitcnt vmcnt(8)
	s_waitcnt lgkmcnt(0)
	s_barrier
	s_waitcnt lgkmcnt(0)
	v_mfma_f32_16x16x32_bf16 v[126:129], v[164:167], v[196:199], v[126:129]
	v_mfma_f32_16x16x32_bf16 v[122:125], v[172:175], v[196:199], v[122:125]
	v_mfma_f32_16x16x32_bf16 v[118:121], v[164:167], v[204:207], v[118:121]
	v_mfma_f32_16x16x32_bf16 v[114:117], v[172:175], v[204:207], v[114:117]
	v_mfma_f32_16x16x32_bf16 v[110:113], v[164:167], v[236:239], v[110:113]
	v_mfma_f32_16x16x32_bf16 v[106:109], v[172:175], v[236:239], v[106:109]
	v_mfma_f32_16x16x32_bf16 v[102:105], v[164:167], v[244:247], v[102:105]
	v_mfma_f32_16x16x32_bf16 v[98:101], v[172:175], v[244:247], v[98:101]
	v_mfma_f32_16x16x32_bf16 v[126:129], v[168:171], v[200:203], v[126:129]
	v_mfma_f32_16x16x32_bf16 v[122:125], v[176:179], v[200:203], v[122:125]
	v_mfma_f32_16x16x32_bf16 v[118:121], v[168:171], v[220:223], v[118:121]
	v_mfma_f32_16x16x32_bf16 v[114:117], v[176:179], v[220:223], v[114:117]
	v_mfma_f32_16x16x32_bf16 v[110:113], v[168:171], v[240:243], v[110:113]
	v_mfma_f32_16x16x32_bf16 v[106:109], v[176:179], v[240:243], v[106:109]
	v_mfma_f32_16x16x32_bf16 v[102:105], v[168:171], v[248:251], v[102:105]
	v_mfma_f32_16x16x32_bf16 v[98:101], v[176:179], v[248:251], v[98:101]
	v_mfma_f32_16x16x32_bf16 v[94:97], v[180:183], v[196:199], v[94:97]
	v_mfma_f32_16x16x32_bf16 v[90:93], v[188:191], v[196:199], v[90:93]
	v_mfma_f32_16x16x32_bf16 v[86:89], v[180:183], v[204:207], v[86:89]
	v_mfma_f32_16x16x32_bf16 v[82:85], v[188:191], v[204:207], v[82:85]
	v_mfma_f32_16x16x32_bf16 v[78:81], v[180:183], v[236:239], v[78:81]
	v_mfma_f32_16x16x32_bf16 v[74:77], v[188:191], v[236:239], v[74:77]
	v_mfma_f32_16x16x32_bf16 v[70:73], v[180:183], v[244:247], v[70:73]
	v_mfma_f32_16x16x32_bf16 v[66:69], v[188:191], v[244:247], v[66:69]
	v_mfma_f32_16x16x32_bf16 v[94:97], v[184:187], v[200:203], v[94:97]
	v_mfma_f32_16x16x32_bf16 v[90:93], v[192:195], v[200:203], v[90:93]
	v_mfma_f32_16x16x32_bf16 v[86:89], v[184:187], v[220:223], v[86:89]
	v_mfma_f32_16x16x32_bf16 v[82:85], v[192:195], v[220:223], v[82:85]
	v_mfma_f32_16x16x32_bf16 v[78:81], v[184:187], v[240:243], v[78:81]
	v_mfma_f32_16x16x32_bf16 v[74:77], v[192:195], v[240:243], v[74:77]
	v_mfma_f32_16x16x32_bf16 v[70:73], v[184:187], v[248:251], v[70:73]
	v_mfma_f32_16x16x32_bf16 v[66:69], v[192:195], v[248:251], v[66:69]
	s_barrier
	s_add_i32 s24, s46, s28
	v_lshl_add_u64 v[150:151], v[150:151], 0, s[96:97]
	s_mov_b32 m0, s24
	ds_read_b128 v[196:199], v162 offset:49152
	ds_read_b128 v[200:203], v162 offset:50176
	ds_read_b128 v[204:207], v162 offset:51200
	ds_read_b128 v[220:223], v162 offset:52224
	ds_read_b128 v[236:239], v162 offset:53248
	ds_read_b128 v[240:243], v162 offset:54272
	ds_read_b128 v[244:247], v162 offset:55296
	ds_read_b128 v[248:251], v162 offset:56320
	global_load_lds_dwordx4 v[150:151], off
	s_add_i32 m0, s24, 0x2000
	s_add_u32 s22, s22, 0x40080
	v_lshl_add_u64 v[150:151], v[208:209], 0, s[96:97]
	s_addc_u32 s23, s23, 0
	s_add_i32 s24, s47, s28
	global_load_lds_dwordx4 v[150:151], off
	v_lshl_add_u64 v[150:151], s[22:23], 0, v[134:135]
	s_mov_b32 m0, s24
	s_nop 0
	global_load_lds_dwordx4 v[150:151], off
	v_lshl_add_u64 v[150:151], s[22:23], 0, v[130:131]
	s_add_i32 m0, s24, 0x2000
	s_nop 0
	global_load_lds_dwordx4 v[150:151], off
	v_lshl_add_u64 v[150:151], v[224:225], 0, s[96:97]
	s_mov_b32 m0, s36
	s_nop 0
	global_load_lds_dwordx4 v[150:151], off
	v_lshl_add_u64 v[150:151], v[252:253], 0, s[96:97]
	s_mov_b32 m0, s37
	s_nop 0
	global_load_lds_dwordx4 v[150:151], off
	s_nop 0
	s_nop 0
	s_waitcnt vmcnt(8)
	s_waitcnt lgkmcnt(0)
	s_barrier
	s_waitcnt lgkmcnt(0)
	v_mfma_f32_16x16x32_bf16 v[62:65], v[164:167], v[196:199], v[62:65]
	v_mfma_f32_16x16x32_bf16 v[58:61], v[172:175], v[196:199], v[58:61]
	v_mfma_f32_16x16x32_bf16 v[54:57], v[164:167], v[204:207], v[54:57]
	v_mfma_f32_16x16x32_bf16 v[50:53], v[172:175], v[204:207], v[50:53]
	v_mfma_f32_16x16x32_bf16 v[46:49], v[164:167], v[236:239], v[46:49]
	v_mfma_f32_16x16x32_bf16 v[42:45], v[172:175], v[236:239], v[42:45]
	v_mfma_f32_16x16x32_bf16 v[38:41], v[164:167], v[244:247], v[38:41]
	v_mfma_f32_16x16x32_bf16 v[34:37], v[172:175], v[244:247], v[34:37]
	v_mfma_f32_16x16x32_bf16 v[62:65], v[168:171], v[200:203], v[62:65]
	v_mfma_f32_16x16x32_bf16 v[58:61], v[176:179], v[200:203], v[58:61]
	v_mfma_f32_16x16x32_bf16 v[54:57], v[168:171], v[220:223], v[54:57]
	v_mfma_f32_16x16x32_bf16 v[50:53], v[176:179], v[220:223], v[50:53]
	v_mfma_f32_16x16x32_bf16 v[46:49], v[168:171], v[240:243], v[46:49]
	v_mfma_f32_16x16x32_bf16 v[42:45], v[176:179], v[240:243], v[42:45]
	v_mfma_f32_16x16x32_bf16 v[38:41], v[168:171], v[248:251], v[38:41]
	v_mfma_f32_16x16x32_bf16 v[34:37], v[176:179], v[248:251], v[34:37]
	v_mfma_f32_16x16x32_bf16 v[30:33], v[180:183], v[196:199], v[30:33]
	v_mfma_f32_16x16x32_bf16 v[26:29], v[188:191], v[196:199], v[26:29]
	v_mfma_f32_16x16x32_bf16 v[22:25], v[180:183], v[204:207], v[22:25]
	v_mfma_f32_16x16x32_bf16 v[18:21], v[188:191], v[204:207], v[18:21]
	v_mfma_f32_16x16x32_bf16 v[14:17], v[180:183], v[236:239], v[14:17]
	v_mfma_f32_16x16x32_bf16 v[10:13], v[188:191], v[236:239], v[10:13]
	v_mfma_f32_16x16x32_bf16 v[6:9], v[180:183], v[244:247], v[6:9]
	v_mfma_f32_16x16x32_bf16 v[2:5], v[188:191], v[244:247], v[2:5]
	v_mfma_f32_16x16x32_bf16 v[30:33], v[184:187], v[200:203], v[30:33]
	v_mfma_f32_16x16x32_bf16 v[26:29], v[192:195], v[200:203], v[26:29]
	v_mfma_f32_16x16x32_bf16 v[22:25], v[184:187], v[220:223], v[22:25]
	v_mfma_f32_16x16x32_bf16 v[18:21], v[192:195], v[220:223], v[18:21]
	v_mfma_f32_16x16x32_bf16 v[14:17], v[184:187], v[240:243], v[14:17]
	v_mfma_f32_16x16x32_bf16 v[10:13], v[192:195], v[240:243], v[10:13]
	v_mfma_f32_16x16x32_bf16 v[6:9], v[184:187], v[248:251], v[6:9]
	v_mfma_f32_16x16x32_bf16 v[2:5], v[192:195], v[248:251], v[2:5]
	s_barrier
	s_add_i32 s45, s45, 2
	s_add_u32 s43, s43, 0x100
	s_addc_u32 s44, s44, 0
	s_add_u32 s20, s20, 0x100
	s_addc_u32 s21, s21, 0
	s_cmp_gt_u32 s45, 13
